# residual GEMM epilogues (FFN1 down, second W_out, FFN2 down): base tile read three groups ahead with counted vmcnt, stores left in flight
# speedup vs baseline: 1.0037x; 1.0037x over previous
.LBB0_449:
	v_lshl_add_u32 v140, s6, 8, v131
	v_lshl_or_b32 v138, s7, 8, v151
	v_ashrrev_i32_e32 v141, 31, v140
	v_ashrrev_i32_e32 v139, 31, v138
	v_lshlrev_b64 v[142:143], 10, v[140:141]
	v_lshl_add_u64 v[142:143], v[142:143], 0, v[138:139]
	v_lshlrev_b64 v[142:143], 2, v[142:143]
	v_mov_b32_e32 v189, v142
	v_lshl_add_u64 v[144:145], s[68:69], 0, v[142:143]
	s_add_u32 s98, s68, 0x0
	s_addc_u32 s99, s69, 0
	global_load_dwordx4 v[212:215], v189, s[98:99]
	global_load_dwordx4 v[216:219], v189, s[98:99] offset:16
	s_add_u32 s98, s68, 0x0
	s_addc_u32 s99, s69, 0
	global_load_dwordx4 v[220:223], v189, s[98:99] offset:512
	global_load_dwordx4 v[224:227], v189, s[98:99] offset:528
	s_add_u32 s98, s68, 0x10000
	s_addc_u32 s99, s69, 0
	global_load_dwordx4 v[228:231], v189, s[98:99]
	global_load_dwordx4 v[232:235], v189, s[98:99] offset:16
	s_add_u32 s98, s68, 0x10000
	s_addc_u32 s99, s69, 0
	global_load_dwordx4 v[244:247], v189, s[98:99] offset:512
	global_load_dwordx4 v[248:251], v189, s[98:99] offset:528
	v_cndmask_b32_e64 v170, 0, 1, s[80:81]
	v_cmp_ne_u32_e64 s[8:9], 1, v170
	v_lshlrev_b64 v[170:171], 11, v[140:141]
	v_lshl_add_u64 v[186:187], s[28:29], 0, v[170:171]
	s_andn2_b64 vcc, exec, s[80:81]
	v_lshl_add_u64 v[170:171], s[26:27], 0, v[142:143]
	v_lshl_add_u64 v[142:143], v[138:139], 1, v[186:187]
	s_waitcnt vmcnt(6)
	v_pk_fma_f32 v[128:129], v[128:129], 0.5, v[214:215] op_sel_hi:[1,0,1]
	v_pk_fma_f32 v[126:127], v[126:127], 0.5, v[212:213] op_sel_hi:[1,0,1]
	v_pk_fma_f32 v[124:125], v[124:125], 0.5, v[218:219] op_sel_hi:[1,0,1]
	v_pk_fma_f32 v[122:123], v[122:123], 0.5, v[216:217] op_sel_hi:[1,0,1]
	global_store_dwordx4 v[170:171], v[126:129], off
	global_store_dwordx4 v[170:171], v[122:125], off offset:16
	s_cbranch_vccnz .LBB0_451
	v_cvt_pk_bf16_f32 v174, v126, v127
	v_cvt_pk_bf16_f32 v175, v128, v129
	v_cvt_pk_bf16_f32 v176, v122, v123
	v_cvt_pk_bf16_f32 v177, v124, v125
	global_store_dwordx4 v[142:143], v[174:177], off
.LBB0_451:
	s_add_u32 s98, s68, 0x20000
	s_addc_u32 s99, s69, 0
	global_load_dwordx4 v[212:215], v189, s[98:99]
	global_load_dwordx4 v[216:219], v189, s[98:99] offset:16
	s_and_b64 vcc, exec, s[8:9]
	s_waitcnt vmcnt(8)
	v_pk_fma_f32 v[120:121], v[120:121], 0.5, v[222:223] op_sel_hi:[1,0,1]
	v_pk_fma_f32 v[118:119], v[118:119], 0.5, v[220:221] op_sel_hi:[1,0,1]
	v_pk_fma_f32 v[116:117], v[116:117], 0.5, v[226:227] op_sel_hi:[1,0,1]
	v_pk_fma_f32 v[114:115], v[114:115], 0.5, v[224:225] op_sel_hi:[1,0,1]
	global_store_dwordx4 v[170:171], v[118:121], off offset:512
	global_store_dwordx4 v[170:171], v[114:117], off offset:528
	s_cbranch_vccnz .LBB0_453
	v_cvt_pk_bf16_f32 v174, v118, v119
	v_cvt_pk_bf16_f32 v175, v120, v121
	v_cvt_pk_bf16_f32 v176, v114, v115
	v_cvt_pk_bf16_f32 v177, v116, v117
	global_store_dwordx4 v[142:143], v[174:177], off offset:256

.LBB0_457:
	v_or_b32_e32 v114, 16, v140
	s_waitcnt lgkmcnt(0)
	v_ashrrev_i32_e32 v115, 31, v114
	v_lshlrev_b64 v[116:117], 10, v[114:115]
	v_lshl_add_u64 v[116:117], v[116:117], 0, v[138:139]
	v_lshlrev_b64 v[116:117], 2, v[116:117]
	v_lshl_add_u64 v[118:119], s[68:69], 0, v[116:117]
	s_add_u32 s98, s68, 0x20000
	s_addc_u32 s99, s69, 0
	global_load_dwordx4 v[220:223], v189, s[98:99] offset:512
	global_load_dwordx4 v[224:227], v189, s[98:99] offset:528
	v_lshlrev_b64 v[120:121], 11, v[114:115]
	v_lshl_add_u64 v[142:143], s[28:29], 0, v[120:121]
	s_and_b64 vcc, exec, s[8:9]
	v_lshl_add_u64 v[120:121], s[26:27], 0, v[116:117]
	v_lshl_add_u64 v[116:117], v[138:139], 1, v[142:143]
	s_waitcnt vmcnt(10)
	v_pk_fma_f32 v[112:113], v[112:113], 0.5, v[230:231] op_sel_hi:[1,0,1]
	v_pk_fma_f32 v[110:111], v[110:111], 0.5, v[228:229] op_sel_hi:[1,0,1]
	v_pk_fma_f32 v[108:109], v[108:109], 0.5, v[234:235] op_sel_hi:[1,0,1]
	v_pk_fma_f32 v[106:107], v[106:107], 0.5, v[232:233] op_sel_hi:[1,0,1]
	global_store_dwordx4 v[120:121], v[110:113], off
	global_store_dwordx4 v[120:121], v[106:109], off offset:16
	s_cbranch_vccnz .LBB0_459
	v_cvt_pk_bf16_f32 v122, v110, v111
	v_cvt_pk_bf16_f32 v123, v112, v113
	v_cvt_pk_bf16_f32 v124, v106, v107
	v_cvt_pk_bf16_f32 v125, v108, v109
	global_store_dwordx4 v[116:117], v[122:125], off
.LBB0_459:
	s_add_u32 s98, s68, 0x30000
	s_addc_u32 s99, s69, 0
	global_load_dwordx4 v[228:231], v189, s[98:99]
	global_load_dwordx4 v[232:235], v189, s[98:99] offset:16
	s_and_b64 vcc, exec, s[8:9]
	s_waitcnt vmcnt(12)
	v_pk_fma_f32 v[104:105], v[104:105], 0.5, v[246:247] op_sel_hi:[1,0,1]
	v_pk_fma_f32 v[102:103], v[102:103], 0.5, v[244:245] op_sel_hi:[1,0,1]
	v_pk_fma_f32 v[100:101], v[100:101], 0.5, v[250:251] op_sel_hi:[1,0,1]
	v_pk_fma_f32 v[98:99], v[98:99], 0.5, v[248:249] op_sel_hi:[1,0,1]
	global_store_dwordx4 v[120:121], v[102:105], off offset:512
	global_store_dwordx4 v[120:121], v[98:101], off offset:528
	s_cbranch_vccnz .LBB0_461
	v_cvt_pk_bf16_f32 v118, v102, v103
	v_cvt_pk_bf16_f32 v119, v104, v105
	v_cvt_pk_bf16_f32 v120, v98, v99
	v_cvt_pk_bf16_f32 v121, v100, v101
	global_store_dwordx4 v[116:117], v[118:121], off offset:256

.LBB0_465:
	v_or_b32_e32 v98, 32, v140
	s_waitcnt lgkmcnt(0)
	v_ashrrev_i32_e32 v99, 31, v98
	v_lshlrev_b64 v[100:101], 10, v[98:99]
	v_lshl_add_u64 v[100:101], v[100:101], 0, v[138:139]
	v_lshlrev_b64 v[100:101], 2, v[100:101]
	v_lshl_add_u64 v[102:103], s[68:69], 0, v[100:101]
	s_add_u32 s98, s68, 0x30000
	s_addc_u32 s99, s69, 0
	global_load_dwordx4 v[244:247], v189, s[98:99] offset:512
	global_load_dwordx4 v[248:251], v189, s[98:99] offset:528
	v_lshlrev_b64 v[104:105], 11, v[98:99]
	v_lshl_add_u64 v[114:115], s[28:29], 0, v[104:105]
	s_and_b64 vcc, exec, s[8:9]
	v_lshl_add_u64 v[104:105], s[26:27], 0, v[100:101]
	v_lshl_add_u64 v[100:101], v[138:139], 1, v[114:115]
	s_waitcnt vmcnt(12)
	v_pk_fma_f32 v[96:97], v[96:97], 0.5, v[214:215] op_sel_hi:[1,0,1]
	v_pk_fma_f32 v[94:95], v[94:95], 0.5, v[212:213] op_sel_hi:[1,0,1]
	v_pk_fma_f32 v[92:93], v[92:93], 0.5, v[218:219] op_sel_hi:[1,0,1]
	v_pk_fma_f32 v[90:91], v[90:91], 0.5, v[216:217] op_sel_hi:[1,0,1]
	global_store_dwordx4 v[104:105], v[94:97], off
	global_store_dwordx4 v[104:105], v[90:93], off offset:16
	s_cbranch_vccnz .LBB0_467
	v_cvt_pk_bf16_f32 v106, v94, v95
	v_cvt_pk_bf16_f32 v107, v96, v97
	v_cvt_pk_bf16_f32 v108, v90, v91
	v_cvt_pk_bf16_f32 v109, v92, v93
	global_store_dwordx4 v[100:101], v[106:109], off
.LBB0_467:
	s_add_u32 s98, s68, 0x80000
	s_addc_u32 s99, s69, 0
	global_load_dwordx4 v[212:215], v189, s[98:99]
	global_load_dwordx4 v[216:219], v189, s[98:99] offset:16
	s_and_b64 vcc, exec, s[8:9]
	s_waitcnt vmcnt(12)
	v_pk_fma_f32 v[88:89], v[88:89], 0.5, v[222:223] op_sel_hi:[1,0,1]
	v_pk_fma_f32 v[86:87], v[86:87], 0.5, v[220:221] op_sel_hi:[1,0,1]
	v_pk_fma_f32 v[84:85], v[84:85], 0.5, v[226:227] op_sel_hi:[1,0,1]
	v_pk_fma_f32 v[82:83], v[82:83], 0.5, v[224:225] op_sel_hi:[1,0,1]
	global_store_dwordx4 v[104:105], v[86:89], off offset:512
	global_store_dwordx4 v[104:105], v[82:85], off offset:528
	s_cbranch_vccnz .LBB0_469
	v_cvt_pk_bf16_f32 v102, v86, v87
	v_cvt_pk_bf16_f32 v103, v88, v89
	v_cvt_pk_bf16_f32 v104, v82, v83
	v_cvt_pk_bf16_f32 v105, v84, v85
	global_store_dwordx4 v[100:101], v[102:105], off offset:256

.LBB0_473:
	v_or_b32_e32 v82, 48, v140
	s_waitcnt lgkmcnt(0)
	v_ashrrev_i32_e32 v83, 31, v82
	v_lshlrev_b64 v[84:85], 10, v[82:83]
	v_lshl_add_u64 v[84:85], v[84:85], 0, v[138:139]
	v_lshlrev_b64 v[84:85], 2, v[84:85]
	v_lshl_add_u64 v[86:87], s[68:69], 0, v[84:85]
	s_add_u32 s98, s68, 0x80000
	s_addc_u32 s99, s69, 0
	global_load_dwordx4 v[220:223], v189, s[98:99] offset:512
	global_load_dwordx4 v[224:227], v189, s[98:99] offset:528
	v_lshlrev_b64 v[88:89], 11, v[82:83]
	v_lshl_add_u64 v[98:99], s[28:29], 0, v[88:89]
	s_and_b64 vcc, exec, s[8:9]
	v_lshl_add_u64 v[88:89], s[26:27], 0, v[84:85]
	v_lshl_add_u64 v[84:85], v[138:139], 1, v[98:99]
	s_waitcnt vmcnt(12)
	v_pk_fma_f32 v[80:81], v[80:81], 0.5, v[230:231] op_sel_hi:[1,0,1]
	v_pk_fma_f32 v[78:79], v[78:79], 0.5, v[228:229] op_sel_hi:[1,0,1]
	v_pk_fma_f32 v[76:77], v[76:77], 0.5, v[234:235] op_sel_hi:[1,0,1]
	v_pk_fma_f32 v[74:75], v[74:75], 0.5, v[232:233] op_sel_hi:[1,0,1]
	global_store_dwordx4 v[88:89], v[78:81], off
	global_store_dwordx4 v[88:89], v[74:77], off offset:16
	s_cbranch_vccnz .LBB0_475
	v_cvt_pk_bf16_f32 v90, v78, v79
	v_cvt_pk_bf16_f32 v91, v80, v81
	v_cvt_pk_bf16_f32 v92, v74, v75
	v_cvt_pk_bf16_f32 v93, v76, v77
	global_store_dwordx4 v[84:85], v[90:93], off
.LBB0_475:
	s_add_u32 s98, s68, 0x90000
	s_addc_u32 s99, s69, 0
	global_load_dwordx4 v[228:231], v189, s[98:99]
	global_load_dwordx4 v[232:235], v189, s[98:99] offset:16
	s_and_b64 vcc, exec, s[8:9]
	s_waitcnt vmcnt(12)
	v_pk_fma_f32 v[72:73], v[72:73], 0.5, v[246:247] op_sel_hi:[1,0,1]
	v_pk_fma_f32 v[70:71], v[70:71], 0.5, v[244:245] op_sel_hi:[1,0,1]
	v_pk_fma_f32 v[68:69], v[68:69], 0.5, v[250:251] op_sel_hi:[1,0,1]
	v_pk_fma_f32 v[66:67], v[66:67], 0.5, v[248:249] op_sel_hi:[1,0,1]
	global_store_dwordx4 v[88:89], v[70:73], off offset:512
	global_store_dwordx4 v[88:89], v[66:69], off offset:528
	s_cbranch_vccnz .LBB0_477
	v_cvt_pk_bf16_f32 v86, v70, v71
	v_cvt_pk_bf16_f32 v87, v72, v73
	v_cvt_pk_bf16_f32 v88, v66, v67
	v_cvt_pk_bf16_f32 v89, v68, v69
	global_store_dwordx4 v[84:85], v[86:89], off offset:256

.LBB0_481:
	v_add_u32_e32 v66, 0x80, v140
	s_waitcnt lgkmcnt(0)
	v_ashrrev_i32_e32 v67, 31, v66
	v_lshlrev_b64 v[68:69], 10, v[66:67]
	v_lshl_add_u64 v[68:69], v[68:69], 0, v[138:139]
	v_lshlrev_b64 v[68:69], 2, v[68:69]
	v_lshl_add_u64 v[70:71], s[68:69], 0, v[68:69]
	s_add_u32 s98, s68, 0x90000
	s_addc_u32 s99, s69, 0
	global_load_dwordx4 v[244:247], v189, s[98:99] offset:512
	global_load_dwordx4 v[248:251], v189, s[98:99] offset:528
	v_lshlrev_b64 v[72:73], 11, v[66:67]
	v_lshl_add_u64 v[82:83], s[28:29], 0, v[72:73]
	s_and_b64 vcc, exec, s[8:9]
	v_lshl_add_u64 v[72:73], s[26:27], 0, v[68:69]
	v_lshl_add_u64 v[68:69], v[138:139], 1, v[82:83]
	s_waitcnt vmcnt(12)
	v_pk_fma_f32 v[64:65], v[64:65], 0.5, v[214:215] op_sel_hi:[1,0,1]
	v_pk_fma_f32 v[62:63], v[62:63], 0.5, v[212:213] op_sel_hi:[1,0,1]
	v_pk_fma_f32 v[60:61], v[60:61], 0.5, v[218:219] op_sel_hi:[1,0,1]
	v_pk_fma_f32 v[58:59], v[58:59], 0.5, v[216:217] op_sel_hi:[1,0,1]
	global_store_dwordx4 v[72:73], v[62:65], off
	global_store_dwordx4 v[72:73], v[58:61], off offset:16
	s_cbranch_vccnz .LBB0_483
	v_cvt_pk_bf16_f32 v74, v62, v63
	v_cvt_pk_bf16_f32 v75, v64, v65
	v_cvt_pk_bf16_f32 v76, v58, v59
	v_cvt_pk_bf16_f32 v77, v60, v61
	global_store_dwordx4 v[68:69], v[74:77], off
.LBB0_483:
	s_add_u32 s98, s68, 0xa0000
	s_addc_u32 s99, s69, 0
	global_load_dwordx4 v[212:215], v189, s[98:99]
	global_load_dwordx4 v[216:219], v189, s[98:99] offset:16
	s_and_b64 vcc, exec, s[8:9]
	s_waitcnt vmcnt(12)
	v_pk_fma_f32 v[56:57], v[56:57], 0.5, v[222:223] op_sel_hi:[1,0,1]
	v_pk_fma_f32 v[54:55], v[54:55], 0.5, v[220:221] op_sel_hi:[1,0,1]
	v_pk_fma_f32 v[52:53], v[52:53], 0.5, v[226:227] op_sel_hi:[1,0,1]
	v_pk_fma_f32 v[50:51], v[50:51], 0.5, v[224:225] op_sel_hi:[1,0,1]
	global_store_dwordx4 v[72:73], v[54:57], off offset:512
	global_store_dwordx4 v[72:73], v[50:53], off offset:528
	s_cbranch_vccnz .LBB0_485
	v_cvt_pk_bf16_f32 v70, v54, v55
	v_cvt_pk_bf16_f32 v71, v56, v57
	v_cvt_pk_bf16_f32 v72, v50, v51
	v_cvt_pk_bf16_f32 v73, v52, v53
	global_store_dwordx4 v[68:69], v[70:73], off offset:256

.LBB0_489:
	v_add_u32_e32 v50, 0x90, v140
	s_waitcnt lgkmcnt(0)
	v_ashrrev_i32_e32 v51, 31, v50
	v_lshlrev_b64 v[52:53], 10, v[50:51]
	v_lshl_add_u64 v[52:53], v[52:53], 0, v[138:139]
	v_lshlrev_b64 v[52:53], 2, v[52:53]
	v_lshl_add_u64 v[54:55], s[68:69], 0, v[52:53]
	s_add_u32 s98, s68, 0xa0000
	s_addc_u32 s99, s69, 0
	global_load_dwordx4 v[220:223], v189, s[98:99] offset:512
	global_load_dwordx4 v[224:227], v189, s[98:99] offset:528
	v_lshlrev_b64 v[56:57], 11, v[50:51]
	v_lshl_add_u64 v[66:67], s[28:29], 0, v[56:57]
	s_and_b64 vcc, exec, s[8:9]
	v_lshl_add_u64 v[56:57], s[26:27], 0, v[52:53]
	v_lshl_add_u64 v[52:53], v[138:139], 1, v[66:67]
	s_waitcnt vmcnt(12)
	v_pk_fma_f32 v[48:49], v[48:49], 0.5, v[230:231] op_sel_hi:[1,0,1]
	v_pk_fma_f32 v[46:47], v[46:47], 0.5, v[228:229] op_sel_hi:[1,0,1]
	v_pk_fma_f32 v[44:45], v[44:45], 0.5, v[234:235] op_sel_hi:[1,0,1]
	v_pk_fma_f32 v[42:43], v[42:43], 0.5, v[232:233] op_sel_hi:[1,0,1]
	global_store_dwordx4 v[56:57], v[46:49], off
	global_store_dwordx4 v[56:57], v[42:45], off offset:16
	s_cbranch_vccnz .LBB0_491
	v_cvt_pk_bf16_f32 v58, v46, v47
	v_cvt_pk_bf16_f32 v59, v48, v49
	v_cvt_pk_bf16_f32 v60, v42, v43
	v_cvt_pk_bf16_f32 v61, v44, v45
	global_store_dwordx4 v[52:53], v[58:61], off
.LBB0_491:
	s_add_u32 s98, s68, 0xb0000
	s_addc_u32 s99, s69, 0
	global_load_dwordx4 v[228:231], v189, s[98:99]
	global_load_dwordx4 v[232:235], v189, s[98:99] offset:16
	s_and_b64 vcc, exec, s[8:9]
	s_waitcnt vmcnt(12)
	v_pk_fma_f32 v[40:41], v[40:41], 0.5, v[246:247] op_sel_hi:[1,0,1]
	v_pk_fma_f32 v[38:39], v[38:39], 0.5, v[244:245] op_sel_hi:[1,0,1]
	v_pk_fma_f32 v[36:37], v[36:37], 0.5, v[250:251] op_sel_hi:[1,0,1]
	v_pk_fma_f32 v[34:35], v[34:35], 0.5, v[248:249] op_sel_hi:[1,0,1]
	global_store_dwordx4 v[56:57], v[38:41], off offset:512
	global_store_dwordx4 v[56:57], v[34:37], off offset:528
	s_cbranch_vccnz .LBB0_493
	v_cvt_pk_bf16_f32 v54, v38, v39
	v_cvt_pk_bf16_f32 v55, v40, v41
	v_cvt_pk_bf16_f32 v56, v34, v35
	v_cvt_pk_bf16_f32 v57, v36, v37
	global_store_dwordx4 v[52:53], v[54:57], off offset:256

.LBB0_497:
	v_add_u32_e32 v34, 0xa0, v140
	s_waitcnt lgkmcnt(0)
	v_ashrrev_i32_e32 v35, 31, v34
	v_lshlrev_b64 v[36:37], 10, v[34:35]
	v_lshl_add_u64 v[36:37], v[36:37], 0, v[138:139]
	v_lshlrev_b64 v[36:37], 2, v[36:37]
	v_lshl_add_u64 v[38:39], s[68:69], 0, v[36:37]
	s_add_u32 s98, s68, 0xb0000
	s_addc_u32 s99, s69, 0
	global_load_dwordx4 v[244:247], v189, s[98:99] offset:512
	global_load_dwordx4 v[248:251], v189, s[98:99] offset:528
	v_lshlrev_b64 v[40:41], 11, v[34:35]
	v_lshl_add_u64 v[50:51], s[28:29], 0, v[40:41]
	s_and_b64 vcc, exec, s[8:9]
	v_lshl_add_u64 v[40:41], s[26:27], 0, v[36:37]
	v_lshl_add_u64 v[36:37], v[138:139], 1, v[50:51]
	s_waitcnt vmcnt(12)
	v_pk_fma_f32 v[32:33], v[32:33], 0.5, v[214:215] op_sel_hi:[1,0,1]
	v_pk_fma_f32 v[30:31], v[30:31], 0.5, v[212:213] op_sel_hi:[1,0,1]
	v_pk_fma_f32 v[28:29], v[28:29], 0.5, v[218:219] op_sel_hi:[1,0,1]
	v_pk_fma_f32 v[26:27], v[26:27], 0.5, v[216:217] op_sel_hi:[1,0,1]
	global_store_dwordx4 v[40:41], v[30:33], off
	global_store_dwordx4 v[40:41], v[26:29], off offset:16
	s_cbranch_vccnz .LBB0_499
	v_cvt_pk_bf16_f32 v42, v30, v31
	v_cvt_pk_bf16_f32 v43, v32, v33
	v_cvt_pk_bf16_f32 v44, v26, v27
	v_cvt_pk_bf16_f32 v45, v28, v29
	global_store_dwordx4 v[36:37], v[42:45], off
.LBB0_499:
	s_and_b64 vcc, exec, s[8:9]
	s_waitcnt vmcnt(10)
	v_pk_fma_f32 v[24:25], v[24:25], 0.5, v[222:223] op_sel_hi:[1,0,1]
	v_pk_fma_f32 v[22:23], v[22:23], 0.5, v[220:221] op_sel_hi:[1,0,1]
	v_pk_fma_f32 v[20:21], v[20:21], 0.5, v[226:227] op_sel_hi:[1,0,1]
	v_pk_fma_f32 v[18:19], v[18:19], 0.5, v[224:225] op_sel_hi:[1,0,1]
	global_store_dwordx4 v[40:41], v[22:25], off offset:512
	global_store_dwordx4 v[40:41], v[18:21], off offset:528
	s_cbranch_vccnz .LBB0_501
	v_cvt_pk_bf16_f32 v38, v22, v23
	v_cvt_pk_bf16_f32 v39, v24, v25
	v_cvt_pk_bf16_f32 v40, v18, v19
	v_cvt_pk_bf16_f32 v41, v20, v21
	global_store_dwordx4 v[36:37], v[38:41], off offset:256

.LBB0_505:
	v_add_u32_e32 v18, 0xb0, v140
	s_waitcnt lgkmcnt(0)
	v_ashrrev_i32_e32 v19, 31, v18
	v_lshlrev_b64 v[20:21], 10, v[18:19]
	v_lshl_add_u64 v[20:21], v[20:21], 0, v[138:139]
	v_lshlrev_b64 v[20:21], 2, v[20:21]
	v_lshl_add_u64 v[22:23], s[68:69], 0, v[20:21]
	v_lshlrev_b64 v[24:25], 11, v[18:19]
	v_lshl_add_u64 v[34:35], s[28:29], 0, v[24:25]
	s_and_b64 vcc, exec, s[8:9]
	v_lshl_add_u64 v[24:25], s[26:27], 0, v[20:21]
	v_lshl_add_u64 v[20:21], v[138:139], 1, v[34:35]
	s_waitcnt vmcnt(8)
	v_pk_fma_f32 v[16:17], v[16:17], 0.5, v[230:231] op_sel_hi:[1,0,1]
	v_pk_fma_f32 v[14:15], v[14:15], 0.5, v[228:229] op_sel_hi:[1,0,1]
	v_pk_fma_f32 v[12:13], v[12:13], 0.5, v[234:235] op_sel_hi:[1,0,1]
	v_pk_fma_f32 v[10:11], v[10:11], 0.5, v[232:233] op_sel_hi:[1,0,1]
	global_store_dwordx4 v[24:25], v[14:17], off
	global_store_dwordx4 v[24:25], v[10:13], off offset:16
	s_cbranch_vccnz .LBB0_507
	v_cvt_pk_bf16_f32 v26, v14, v15
	v_cvt_pk_bf16_f32 v27, v16, v17
	v_cvt_pk_bf16_f32 v28, v10, v11
	v_cvt_pk_bf16_f32 v29, v12, v13
	global_store_dwordx4 v[20:21], v[26:29], off
.LBB0_507:
	s_and_b64 vcc, exec, s[8:9]
	s_waitcnt vmcnt(6)
	v_pk_fma_f32 v[8:9], v[8:9], 0.5, v[246:247] op_sel_hi:[1,0,1]
	v_pk_fma_f32 v[6:7], v[6:7], 0.5, v[244:245] op_sel_hi:[1,0,1]
	v_pk_fma_f32 v[4:5], v[4:5], 0.5, v[250:251] op_sel_hi:[1,0,1]
	v_pk_fma_f32 v[2:3], v[2:3], 0.5, v[248:249] op_sel_hi:[1,0,1]
	global_store_dwordx4 v[24:25], v[6:9], off offset:512
	global_store_dwordx4 v[24:25], v[2:5], off offset:528
	s_cbranch_vccnz .LBB0_509
	v_cvt_pk_bf16_f32 v22, v6, v7
	v_cvt_pk_bf16_f32 v23, v8, v9
	v_cvt_pk_bf16_f32 v24, v2, v3
	v_cvt_pk_bf16_f32 v25, v4, v5
	global_store_dwordx4 v[20:21], v[22:25], off offset:256

.LBB0_1652:
	v_lshl_add_u32 v140, s52, 8, v157
	v_ashrrev_i32_e32 v141, 31, v140
	v_lshl_or_b32 v138, s8, 8, v161
	v_lshlrev_b32_e32 v189, 12, v140
	v_lshl_add_u32 v189, v138, 2, v189
	v_lshlrev_b64 v[142:143], 12, v[140:141]
	v_ashrrev_i32_e32 v139, 31, v138
	v_lshl_add_u64 v[142:143], s[26:27], 0, v[142:143]
	v_lshl_add_u64 v[144:145], v[138:139], 2, v[142:143]
	s_add_u32 s98, s26, 0x0
	s_addc_u32 s99, s27, 0
	global_load_dwordx4 v[212:215], v189, s[98:99]
	global_load_dwordx4 v[216:219], v189, s[98:99] offset:16
	s_add_u32 s98, s26, 0x0
	s_addc_u32 s99, s27, 0
	global_load_dwordx4 v[220:223], v189, s[98:99] offset:512
	global_load_dwordx4 v[224:227], v189, s[98:99] offset:528
	s_add_u32 s98, s26, 0x10000
	s_addc_u32 s99, s27, 0
	global_load_dwordx4 v[228:231], v189, s[98:99]
	global_load_dwordx4 v[232:235], v189, s[98:99] offset:16
	s_add_u32 s98, s26, 0x10000
	s_addc_u32 s99, s27, 0
	global_load_dwordx4 v[244:247], v189, s[98:99] offset:512
	global_load_dwordx4 v[248:251], v189, s[98:99] offset:528
	s_cmp_lt_i32 s52, 32
	s_cselect_b32 s6, s69, 0xffffffd6
	v_cndmask_b32_e64 v142, 0, 1, s[22:23]
	s_add_i32 s6, s6, s52
	v_cmp_ne_u32_e64 s[8:9], 1, v142
	v_lshl_add_u32 v142, s6, 8, v157
	v_ashrrev_i32_e32 v143, 31, v142
	v_lshlrev_b64 v[164:165], 11, v[142:143]
	v_lshl_add_u64 v[164:165], s[40:41], 0, v[164:165]
	s_andn2_b64 vcc, exec, s[22:23]
	v_lshl_add_u64 v[164:165], v[138:139], 1, v[164:165]
	s_waitcnt vmcnt(6)
	v_pk_add_f32 v[128:129], v[128:129], v[214:215]
	v_pk_add_f32 v[126:127], v[126:127], v[212:213]
	v_pk_add_f32 v[124:125], v[124:125], v[218:219]
	v_pk_add_f32 v[122:123], v[122:123], v[216:217]
	global_store_dwordx4 v[144:145], v[126:129], off
	global_store_dwordx4 v[144:145], v[122:125], off offset:16
	s_cbranch_vccnz .LBB0_1654
	v_cvt_pk_bf16_f32 v174, v126, v127
	v_cvt_pk_bf16_f32 v175, v128, v129
	v_cvt_pk_bf16_f32 v176, v122, v123
	v_cvt_pk_bf16_f32 v177, v124, v125
	global_store_dwordx4 v[164:165], v[174:177], off
.LBB0_1654:
	s_add_u32 s98, s26, 0x20000
	s_addc_u32 s99, s27, 0
	global_load_dwordx4 v[212:215], v189, s[98:99]
	global_load_dwordx4 v[216:219], v189, s[98:99] offset:16
	s_and_b64 vcc, exec, s[8:9]
	s_waitcnt vmcnt(8)
	v_pk_add_f32 v[120:121], v[120:121], v[222:223]
	v_pk_add_f32 v[118:119], v[118:119], v[220:221]
	v_pk_add_f32 v[116:117], v[116:117], v[226:227]
	v_pk_add_f32 v[114:115], v[114:115], v[224:225]
	global_store_dwordx4 v[144:145], v[118:121], off offset:512
	global_store_dwordx4 v[144:145], v[114:117], off offset:528
	s_cbranch_vccnz .LBB0_1656
	v_cvt_pk_bf16_f32 v174, v118, v119
	v_cvt_pk_bf16_f32 v175, v120, v121
	v_cvt_pk_bf16_f32 v176, v114, v115
	v_cvt_pk_bf16_f32 v177, v116, v117
	global_store_dwordx4 v[164:165], v[174:177], off offset:256

.LBB0_1660:
	v_or_b32_e32 v114, 16, v140
	s_waitcnt lgkmcnt(0)
	v_ashrrev_i32_e32 v115, 31, v114
	v_lshlrev_b64 v[116:117], 12, v[114:115]
	v_lshl_add_u64 v[116:117], s[26:27], 0, v[116:117]
	v_lshl_add_u64 v[116:117], v[138:139], 2, v[116:117]
	s_add_u32 s98, s26, 0x20000
	s_addc_u32 s99, s27, 0
	global_load_dwordx4 v[220:223], v189, s[98:99] offset:512
	global_load_dwordx4 v[224:227], v189, s[98:99] offset:528
	v_or_b32_e32 v126, 16, v142
	v_ashrrev_i32_e32 v127, 31, v126
	v_lshlrev_b64 v[126:127], 11, v[126:127]
	v_lshl_add_u64 v[126:127], s[40:41], 0, v[126:127]
	s_and_b64 vcc, exec, s[8:9]
	s_waitcnt vmcnt(10)
	v_pk_add_f32 v[112:113], v[112:113], v[230:231]
	v_pk_add_f32 v[110:111], v[110:111], v[228:229]
	v_pk_add_f32 v[108:109], v[108:109], v[234:235]
	v_pk_add_f32 v[106:107], v[106:107], v[232:233]
	v_lshl_add_u64 v[118:119], v[138:139], 1, v[126:127]
	global_store_dwordx4 v[116:117], v[110:113], off
	global_store_dwordx4 v[116:117], v[106:109], off offset:16
	s_cbranch_vccnz .LBB0_1662
	v_cvt_pk_bf16_f32 v120, v110, v111
	v_cvt_pk_bf16_f32 v121, v112, v113
	v_cvt_pk_bf16_f32 v122, v106, v107
	v_cvt_pk_bf16_f32 v123, v108, v109
	global_store_dwordx4 v[118:119], v[120:123], off
.LBB0_1662:
	s_add_u32 s98, s26, 0x30000
	s_addc_u32 s99, s27, 0
	global_load_dwordx4 v[228:231], v189, s[98:99]
	global_load_dwordx4 v[232:235], v189, s[98:99] offset:16
	s_and_b64 vcc, exec, s[8:9]
	s_waitcnt vmcnt(12)
	v_pk_add_f32 v[104:105], v[104:105], v[246:247]
	v_pk_add_f32 v[102:103], v[102:103], v[244:245]
	v_pk_add_f32 v[100:101], v[100:101], v[250:251]
	v_pk_add_f32 v[98:99], v[98:99], v[248:249]
	global_store_dwordx4 v[116:117], v[102:105], off offset:512
	global_store_dwordx4 v[116:117], v[98:101], off offset:528
	s_cbranch_vccnz .LBB0_1664
	v_cvt_pk_bf16_f32 v120, v102, v103
	v_cvt_pk_bf16_f32 v121, v104, v105
	v_cvt_pk_bf16_f32 v122, v98, v99
	v_cvt_pk_bf16_f32 v123, v100, v101
	global_store_dwordx4 v[118:119], v[120:123], off offset:256

.LBB0_1668:
	v_or_b32_e32 v98, 32, v140
	s_waitcnt lgkmcnt(0)
	v_ashrrev_i32_e32 v99, 31, v98
	v_lshlrev_b64 v[100:101], 12, v[98:99]
	v_lshl_add_u64 v[100:101], s[26:27], 0, v[100:101]
	v_lshl_add_u64 v[100:101], v[138:139], 2, v[100:101]
	s_add_u32 s98, s26, 0x30000
	s_addc_u32 s99, s27, 0
	global_load_dwordx4 v[244:247], v189, s[98:99] offset:512
	global_load_dwordx4 v[248:251], v189, s[98:99] offset:528
	v_or_b32_e32 v110, 32, v142
	v_ashrrev_i32_e32 v111, 31, v110
	v_lshlrev_b64 v[110:111], 11, v[110:111]
	v_lshl_add_u64 v[110:111], s[40:41], 0, v[110:111]
	s_and_b64 vcc, exec, s[8:9]
	s_waitcnt vmcnt(12)
	v_pk_add_f32 v[96:97], v[96:97], v[214:215]
	v_pk_add_f32 v[94:95], v[94:95], v[212:213]
	v_pk_add_f32 v[92:93], v[92:93], v[218:219]
	v_pk_add_f32 v[90:91], v[90:91], v[216:217]
	v_lshl_add_u64 v[102:103], v[138:139], 1, v[110:111]
	global_store_dwordx4 v[100:101], v[94:97], off
	global_store_dwordx4 v[100:101], v[90:93], off offset:16
	s_cbranch_vccnz .LBB0_1670
	v_cvt_pk_bf16_f32 v104, v94, v95
	v_cvt_pk_bf16_f32 v105, v96, v97
	v_cvt_pk_bf16_f32 v106, v90, v91
	v_cvt_pk_bf16_f32 v107, v92, v93
	global_store_dwordx4 v[102:103], v[104:107], off
.LBB0_1670:
	s_add_u32 s98, s26, 0x80000
	s_addc_u32 s99, s27, 0
	global_load_dwordx4 v[212:215], v189, s[98:99]
	global_load_dwordx4 v[216:219], v189, s[98:99] offset:16
	s_and_b64 vcc, exec, s[8:9]
	s_waitcnt vmcnt(12)
	v_pk_add_f32 v[88:89], v[88:89], v[222:223]
	v_pk_add_f32 v[86:87], v[86:87], v[220:221]
	v_pk_add_f32 v[84:85], v[84:85], v[226:227]
	v_pk_add_f32 v[82:83], v[82:83], v[224:225]
	global_store_dwordx4 v[100:101], v[86:89], off offset:512
	global_store_dwordx4 v[100:101], v[82:85], off offset:528
	s_cbranch_vccnz .LBB0_1672
	v_cvt_pk_bf16_f32 v104, v86, v87
	v_cvt_pk_bf16_f32 v105, v88, v89
	v_cvt_pk_bf16_f32 v106, v82, v83
	v_cvt_pk_bf16_f32 v107, v84, v85
	global_store_dwordx4 v[102:103], v[104:107], off offset:256

.LBB0_1676:
	v_or_b32_e32 v82, 48, v140
	s_waitcnt lgkmcnt(0)
	v_ashrrev_i32_e32 v83, 31, v82
	v_lshlrev_b64 v[84:85], 12, v[82:83]
	v_lshl_add_u64 v[84:85], s[26:27], 0, v[84:85]
	v_lshl_add_u64 v[84:85], v[138:139], 2, v[84:85]
	s_add_u32 s98, s26, 0x80000
	s_addc_u32 s99, s27, 0
	global_load_dwordx4 v[220:223], v189, s[98:99] offset:512
	global_load_dwordx4 v[224:227], v189, s[98:99] offset:528
	v_or_b32_e32 v94, 48, v142
	v_ashrrev_i32_e32 v95, 31, v94
	v_lshlrev_b64 v[94:95], 11, v[94:95]
	v_lshl_add_u64 v[94:95], s[40:41], 0, v[94:95]
	s_and_b64 vcc, exec, s[8:9]
	s_waitcnt vmcnt(12)
	v_pk_add_f32 v[80:81], v[80:81], v[230:231]
	v_pk_add_f32 v[78:79], v[78:79], v[228:229]
	v_pk_add_f32 v[76:77], v[76:77], v[234:235]
	v_pk_add_f32 v[74:75], v[74:75], v[232:233]
	v_lshl_add_u64 v[86:87], v[138:139], 1, v[94:95]
	global_store_dwordx4 v[84:85], v[78:81], off
	global_store_dwordx4 v[84:85], v[74:77], off offset:16
	s_cbranch_vccnz .LBB0_1678
	v_cvt_pk_bf16_f32 v88, v78, v79
	v_cvt_pk_bf16_f32 v89, v80, v81
	v_cvt_pk_bf16_f32 v90, v74, v75
	v_cvt_pk_bf16_f32 v91, v76, v77
	global_store_dwordx4 v[86:87], v[88:91], off
.LBB0_1678:
	s_add_u32 s98, s26, 0x90000
	s_addc_u32 s99, s27, 0
	global_load_dwordx4 v[228:231], v189, s[98:99]
	global_load_dwordx4 v[232:235], v189, s[98:99] offset:16
	s_and_b64 vcc, exec, s[8:9]
	s_waitcnt vmcnt(12)
	v_pk_add_f32 v[72:73], v[72:73], v[246:247]
	v_pk_add_f32 v[70:71], v[70:71], v[244:245]
	v_pk_add_f32 v[68:69], v[68:69], v[250:251]
	v_pk_add_f32 v[66:67], v[66:67], v[248:249]
	global_store_dwordx4 v[84:85], v[70:73], off offset:512
	global_store_dwordx4 v[84:85], v[66:69], off offset:528
	s_cbranch_vccnz .LBB0_1680
	v_cvt_pk_bf16_f32 v88, v70, v71
	v_cvt_pk_bf16_f32 v89, v72, v73
	v_cvt_pk_bf16_f32 v90, v66, v67
	v_cvt_pk_bf16_f32 v91, v68, v69
	global_store_dwordx4 v[86:87], v[88:91], off offset:256

.LBB0_1684:
	v_add_u32_e32 v66, 0x80, v140
	s_waitcnt lgkmcnt(0)
	v_ashrrev_i32_e32 v67, 31, v66
	v_lshlrev_b64 v[68:69], 12, v[66:67]
	v_lshl_add_u64 v[68:69], s[26:27], 0, v[68:69]
	v_lshl_add_u64 v[68:69], v[138:139], 2, v[68:69]
	s_add_u32 s98, s26, 0x90000
	s_addc_u32 s99, s27, 0
	global_load_dwordx4 v[244:247], v189, s[98:99] offset:512
	global_load_dwordx4 v[248:251], v189, s[98:99] offset:528
	v_lshlrev_b64 v[78:79], 11, v[142:143]
	v_lshl_add_u64 v[78:79], v[78:79], 0, s[12:13]
	v_lshl_add_u64 v[78:79], s[40:41], 0, v[78:79]
	s_and_b64 vcc, exec, s[8:9]
	s_waitcnt vmcnt(12)
	v_pk_add_f32 v[64:65], v[64:65], v[214:215]
	v_pk_add_f32 v[62:63], v[62:63], v[212:213]
	v_pk_add_f32 v[60:61], v[60:61], v[218:219]
	v_pk_add_f32 v[58:59], v[58:59], v[216:217]
	v_lshl_add_u64 v[70:71], v[138:139], 1, v[78:79]
	global_store_dwordx4 v[68:69], v[62:65], off
	global_store_dwordx4 v[68:69], v[58:61], off offset:16
	s_cbranch_vccnz .LBB0_1686
	v_cvt_pk_bf16_f32 v72, v62, v63
	v_cvt_pk_bf16_f32 v73, v64, v65
	v_cvt_pk_bf16_f32 v74, v58, v59
	v_cvt_pk_bf16_f32 v75, v60, v61
	global_store_dwordx4 v[70:71], v[72:75], off
.LBB0_1686:
	s_add_u32 s98, s26, 0xa0000
	s_addc_u32 s99, s27, 0
	global_load_dwordx4 v[212:215], v189, s[98:99]
	global_load_dwordx4 v[216:219], v189, s[98:99] offset:16
	s_and_b64 vcc, exec, s[8:9]
	s_waitcnt vmcnt(12)
	v_pk_add_f32 v[56:57], v[56:57], v[222:223]
	v_pk_add_f32 v[54:55], v[54:55], v[220:221]
	v_pk_add_f32 v[52:53], v[52:53], v[226:227]
	v_pk_add_f32 v[50:51], v[50:51], v[224:225]
	global_store_dwordx4 v[68:69], v[54:57], off offset:512
	global_store_dwordx4 v[68:69], v[50:53], off offset:528
	s_cbranch_vccnz .LBB0_1688
	v_cvt_pk_bf16_f32 v72, v54, v55
	v_cvt_pk_bf16_f32 v73, v56, v57
	v_cvt_pk_bf16_f32 v74, v50, v51
	v_cvt_pk_bf16_f32 v75, v52, v53
	global_store_dwordx4 v[70:71], v[72:75], off offset:256

.LBB0_1692:
	v_add_u32_e32 v50, 0x90, v140
	s_waitcnt lgkmcnt(0)
	v_ashrrev_i32_e32 v51, 31, v50
	v_lshlrev_b64 v[52:53], 12, v[50:51]
	v_lshl_add_u64 v[52:53], s[26:27], 0, v[52:53]
	v_lshl_add_u64 v[52:53], v[138:139], 2, v[52:53]
	s_add_u32 s98, s26, 0xa0000
	s_addc_u32 s99, s27, 0
	global_load_dwordx4 v[220:223], v189, s[98:99] offset:512
	global_load_dwordx4 v[224:227], v189, s[98:99] offset:528
	v_lshlrev_b64 v[62:63], 11, v[142:143]
	v_lshl_add_u64 v[62:63], v[62:63], 0, s[24:25]
	v_lshl_add_u64 v[62:63], s[40:41], 0, v[62:63]
	s_and_b64 vcc, exec, s[8:9]
	s_waitcnt vmcnt(12)
	v_pk_add_f32 v[48:49], v[48:49], v[230:231]
	v_pk_add_f32 v[46:47], v[46:47], v[228:229]
	v_pk_add_f32 v[44:45], v[44:45], v[234:235]
	v_pk_add_f32 v[42:43], v[42:43], v[232:233]
	v_lshl_add_u64 v[54:55], v[138:139], 1, v[62:63]
	global_store_dwordx4 v[52:53], v[46:49], off
	global_store_dwordx4 v[52:53], v[42:45], off offset:16
	s_cbranch_vccnz .LBB0_1694
	v_cvt_pk_bf16_f32 v56, v46, v47
	v_cvt_pk_bf16_f32 v57, v48, v49
	v_cvt_pk_bf16_f32 v58, v42, v43
	v_cvt_pk_bf16_f32 v59, v44, v45
	global_store_dwordx4 v[54:55], v[56:59], off
.LBB0_1694:
	s_add_u32 s98, s26, 0xb0000
	s_addc_u32 s99, s27, 0
	global_load_dwordx4 v[228:231], v189, s[98:99]
	global_load_dwordx4 v[232:235], v189, s[98:99] offset:16
	s_and_b64 vcc, exec, s[8:9]
	s_waitcnt vmcnt(12)
	v_pk_add_f32 v[40:41], v[40:41], v[246:247]
	v_pk_add_f32 v[38:39], v[38:39], v[244:245]
	v_pk_add_f32 v[36:37], v[36:37], v[250:251]
	v_pk_add_f32 v[34:35], v[34:35], v[248:249]
	global_store_dwordx4 v[52:53], v[38:41], off offset:512
	global_store_dwordx4 v[52:53], v[34:37], off offset:528
	s_cbranch_vccnz .LBB0_1696
	v_cvt_pk_bf16_f32 v56, v38, v39
	v_cvt_pk_bf16_f32 v57, v40, v41
	v_cvt_pk_bf16_f32 v58, v34, v35
	v_cvt_pk_bf16_f32 v59, v36, v37
	global_store_dwordx4 v[54:55], v[56:59], off offset:256

.LBB0_1700:
	v_add_u32_e32 v34, 0xa0, v140
	s_waitcnt lgkmcnt(0)
	v_ashrrev_i32_e32 v35, 31, v34
	v_lshlrev_b64 v[36:37], 12, v[34:35]
	v_lshl_add_u64 v[36:37], s[26:27], 0, v[36:37]
	v_lshl_add_u64 v[36:37], v[138:139], 2, v[36:37]
	s_add_u32 s98, s26, 0xb0000
	s_addc_u32 s99, s27, 0
	global_load_dwordx4 v[244:247], v189, s[98:99] offset:512
	global_load_dwordx4 v[248:251], v189, s[98:99] offset:528
	v_lshlrev_b64 v[46:47], 11, v[142:143]
	v_lshl_add_u64 v[46:47], v[46:47], 0, s[34:35]
	v_lshl_add_u64 v[46:47], s[40:41], 0, v[46:47]
	s_and_b64 vcc, exec, s[8:9]
	s_waitcnt vmcnt(12)
	v_pk_add_f32 v[32:33], v[32:33], v[214:215]
	v_pk_add_f32 v[30:31], v[30:31], v[212:213]
	v_pk_add_f32 v[28:29], v[28:29], v[218:219]
	v_pk_add_f32 v[26:27], v[26:27], v[216:217]
	v_lshl_add_u64 v[38:39], v[138:139], 1, v[46:47]
	global_store_dwordx4 v[36:37], v[30:33], off
	global_store_dwordx4 v[36:37], v[26:29], off offset:16
	s_cbranch_vccnz .LBB0_1702
	v_cvt_pk_bf16_f32 v40, v30, v31
	v_cvt_pk_bf16_f32 v41, v32, v33
	v_cvt_pk_bf16_f32 v42, v26, v27
	v_cvt_pk_bf16_f32 v43, v28, v29
	global_store_dwordx4 v[38:39], v[40:43], off
.LBB0_1702:
	s_and_b64 vcc, exec, s[8:9]
	s_waitcnt vmcnt(10)
	v_pk_add_f32 v[24:25], v[24:25], v[222:223]
	v_pk_add_f32 v[22:23], v[22:23], v[220:221]
	v_pk_add_f32 v[20:21], v[20:21], v[226:227]
	v_pk_add_f32 v[18:19], v[18:19], v[224:225]
	global_store_dwordx4 v[36:37], v[22:25], off offset:512
	global_store_dwordx4 v[36:37], v[18:21], off offset:528
	s_cbranch_vccnz .LBB0_1704
	v_cvt_pk_bf16_f32 v40, v22, v23
	v_cvt_pk_bf16_f32 v41, v24, v25
	v_cvt_pk_bf16_f32 v42, v18, v19
	v_cvt_pk_bf16_f32 v43, v20, v21
	global_store_dwordx4 v[38:39], v[40:43], off offset:256

.LBB0_1708:
	v_add_u32_e32 v18, 0xb0, v140
	s_waitcnt lgkmcnt(0)
	v_ashrrev_i32_e32 v19, 31, v18
	v_lshlrev_b64 v[20:21], 12, v[18:19]
	v_lshl_add_u64 v[20:21], s[26:27], 0, v[20:21]
	v_lshl_add_u64 v[20:21], v[138:139], 2, v[20:21]
	v_lshlrev_b64 v[30:31], 11, v[142:143]
	v_lshl_add_u64 v[30:31], v[30:31], 0, s[38:39]
	v_lshl_add_u64 v[30:31], s[40:41], 0, v[30:31]
	s_and_b64 vcc, exec, s[8:9]
	s_waitcnt vmcnt(8)
	v_pk_add_f32 v[16:17], v[16:17], v[230:231]
	v_pk_add_f32 v[14:15], v[14:15], v[228:229]
	v_pk_add_f32 v[12:13], v[12:13], v[234:235]
	v_pk_add_f32 v[10:11], v[10:11], v[232:233]
	v_lshl_add_u64 v[22:23], v[138:139], 1, v[30:31]
	global_store_dwordx4 v[20:21], v[14:17], off
	global_store_dwordx4 v[20:21], v[10:13], off offset:16
	s_cbranch_vccnz .LBB0_1710
	v_cvt_pk_bf16_f32 v24, v14, v15
	v_cvt_pk_bf16_f32 v25, v16, v17
	v_cvt_pk_bf16_f32 v26, v10, v11
	v_cvt_pk_bf16_f32 v27, v12, v13
	global_store_dwordx4 v[22:23], v[24:27], off
.LBB0_1710:
	s_and_b64 vcc, exec, s[8:9]
	s_waitcnt vmcnt(6)
	v_pk_add_f32 v[8:9], v[8:9], v[246:247]
	v_pk_add_f32 v[6:7], v[6:7], v[244:245]
	v_pk_add_f32 v[4:5], v[4:5], v[250:251]
	v_pk_add_f32 v[2:3], v[2:3], v[248:249]
	global_store_dwordx4 v[20:21], v[6:9], off offset:512
	global_store_dwordx4 v[20:21], v[2:5], off offset:528
	s_cbranch_vccnz .LBB0_1712
	v_cvt_pk_bf16_f32 v24, v6, v7
	v_cvt_pk_bf16_f32 v25, v8, v9
	v_cvt_pk_bf16_f32 v26, v2, v3
	v_cvt_pk_bf16_f32 v27, v4, v5
	global_store_dwordx4 v[22:23], v[24:27], off offset:256

.LBB0_1874:
	v_lshl_add_u32 v138, s28, 8, v142
	v_lshl_or_b32 v136, s54, 8, v144
	v_lshlrev_b32_e32 v189, 12, v138
	v_lshl_add_u32 v189, v136, 2, v189
	v_ashrrev_i32_e32 v139, 31, v138
	v_ashrrev_i32_e32 v137, 31, v136
	v_lshlrev_b64 v[140:141], 12, v[138:139]
	v_lshl_add_u64 v[148:149], s[26:27], 0, v[140:141]
	v_lshlrev_b64 v[140:141], 2, v[136:137]
	v_lshl_add_u64 v[136:137], v[148:149], 0, v[140:141]
	s_add_u32 s98, s26, 0x0
	s_addc_u32 s99, s27, 0
	global_load_dwordx4 v[212:215], v189, s[98:99]
	global_load_dwordx4 v[216:219], v189, s[98:99] offset:16
	s_add_u32 s98, s26, 0x0
	s_addc_u32 s99, s27, 0
	global_load_dwordx4 v[220:223], v189, s[98:99] offset:512
	global_load_dwordx4 v[224:227], v189, s[98:99] offset:528
	s_add_u32 s98, s26, 0x10000
	s_addc_u32 s99, s27, 0
	global_load_dwordx4 v[228:231], v189, s[98:99]
	global_load_dwordx4 v[232:235], v189, s[98:99] offset:16
	s_add_u32 s98, s26, 0x10000
	s_addc_u32 s99, s27, 0
	global_load_dwordx4 v[244:247], v189, s[98:99] offset:512
	global_load_dwordx4 v[248:251], v189, s[98:99] offset:528
	s_mov_b64 s[24:25], -1
	s_waitcnt vmcnt(6)
	v_pk_fma_f32 v[122:123], v[122:123], 0.5, v[218:219] op_sel_hi:[1,0,1]
	v_pk_fma_f32 v[126:127], v[126:127], 0.5, v[214:215] op_sel_hi:[1,0,1]
	v_pk_fma_f32 v[124:125], v[124:125], 0.5, v[212:213] op_sel_hi:[1,0,1]
	v_pk_fma_f32 v[120:121], v[120:121], 0.5, v[216:217] op_sel_hi:[1,0,1]
	global_store_dwordx4 v[136:137], v[124:127], off
	global_store_dwordx4 v[136:137], v[120:123], off offset:16
	s_add_u32 s98, s26, 0x20000
	s_addc_u32 s99, s27, 0
	global_load_dwordx4 v[212:215], v189, s[98:99]
	global_load_dwordx4 v[216:219], v189, s[98:99] offset:16
	s_waitcnt vmcnt(8)
	v_pk_fma_f32 v[112:113], v[112:113], 0.5, v[224:225] op_sel_hi:[1,0,1]
	v_pk_fma_f32 v[118:119], v[118:119], 0.5, v[222:223] op_sel_hi:[1,0,1]
	v_pk_fma_f32 v[116:117], v[116:117], 0.5, v[220:221] op_sel_hi:[1,0,1]
	v_pk_fma_f32 v[114:115], v[114:115], 0.5, v[226:227] op_sel_hi:[1,0,1]
	global_store_dwordx4 v[136:137], v[116:119], off offset:512
	global_store_dwordx4 v[136:137], v[112:115], off offset:528
	s_nop 1
	v_or_b32_e32 v112, 16, v138
	v_ashrrev_i32_e32 v113, 31, v112
	v_lshlrev_b64 v[112:113], 12, v[112:113]
	v_lshl_add_u64 v[112:113], s[26:27], 0, v[112:113]
	v_lshl_add_u64 v[120:121], v[112:113], 0, v[140:141]
	s_add_u32 s98, s26, 0x20000
	s_addc_u32 s99, s27, 0
	global_load_dwordx4 v[220:223], v189, s[98:99] offset:512
	global_load_dwordx4 v[224:227], v189, s[98:99] offset:528
	s_waitcnt vmcnt(10)
	v_pk_fma_f32 v[106:107], v[106:107], 0.5, v[234:235] op_sel_hi:[1,0,1]
	v_pk_fma_f32 v[110:111], v[110:111], 0.5, v[230:231] op_sel_hi:[1,0,1]
	v_pk_fma_f32 v[108:109], v[108:109], 0.5, v[228:229] op_sel_hi:[1,0,1]
	v_pk_fma_f32 v[104:105], v[104:105], 0.5, v[232:233] op_sel_hi:[1,0,1]
	global_store_dwordx4 v[120:121], v[108:111], off
	global_store_dwordx4 v[120:121], v[104:107], off offset:16
	s_add_u32 s98, s26, 0x30000
	s_addc_u32 s99, s27, 0
	global_load_dwordx4 v[228:231], v189, s[98:99]
	global_load_dwordx4 v[232:235], v189, s[98:99] offset:16
	s_waitcnt vmcnt(12)
	v_pk_fma_f32 v[96:97], v[96:97], 0.5, v[248:249] op_sel_hi:[1,0,1]
	v_pk_fma_f32 v[102:103], v[102:103], 0.5, v[246:247] op_sel_hi:[1,0,1]
	v_pk_fma_f32 v[100:101], v[100:101], 0.5, v[244:245] op_sel_hi:[1,0,1]
	v_pk_fma_f32 v[98:99], v[98:99], 0.5, v[250:251] op_sel_hi:[1,0,1]
	global_store_dwordx4 v[120:121], v[100:103], off offset:512
	global_store_dwordx4 v[120:121], v[96:99], off offset:528
	s_nop 1
	v_or_b32_e32 v96, 32, v138
	v_ashrrev_i32_e32 v97, 31, v96
	v_lshlrev_b64 v[96:97], 12, v[96:97]
	v_lshl_add_u64 v[96:97], s[26:27], 0, v[96:97]
	v_lshl_add_u64 v[104:105], v[96:97], 0, v[140:141]
	s_add_u32 s98, s26, 0x30000
	s_addc_u32 s99, s27, 0
	global_load_dwordx4 v[244:247], v189, s[98:99] offset:512
	global_load_dwordx4 v[248:251], v189, s[98:99] offset:528
	s_waitcnt vmcnt(12)
	v_pk_fma_f32 v[90:91], v[90:91], 0.5, v[218:219] op_sel_hi:[1,0,1]
	v_pk_fma_f32 v[94:95], v[94:95], 0.5, v[214:215] op_sel_hi:[1,0,1]
	v_pk_fma_f32 v[92:93], v[92:93], 0.5, v[212:213] op_sel_hi:[1,0,1]
	v_pk_fma_f32 v[88:89], v[88:89], 0.5, v[216:217] op_sel_hi:[1,0,1]
	global_store_dwordx4 v[104:105], v[92:95], off
	global_store_dwordx4 v[104:105], v[88:91], off offset:16
	s_add_u32 s98, s26, 0x80000
	s_addc_u32 s99, s27, 0
	global_load_dwordx4 v[212:215], v189, s[98:99]
	global_load_dwordx4 v[216:219], v189, s[98:99] offset:16
	s_waitcnt vmcnt(12)
	v_pk_fma_f32 v[80:81], v[80:81], 0.5, v[224:225] op_sel_hi:[1,0,1]
	v_pk_fma_f32 v[86:87], v[86:87], 0.5, v[222:223] op_sel_hi:[1,0,1]
	v_pk_fma_f32 v[84:85], v[84:85], 0.5, v[220:221] op_sel_hi:[1,0,1]
	v_pk_fma_f32 v[82:83], v[82:83], 0.5, v[226:227] op_sel_hi:[1,0,1]
	global_store_dwordx4 v[104:105], v[84:87], off offset:512
	global_store_dwordx4 v[104:105], v[80:83], off offset:528
	s_nop 1
	v_or_b32_e32 v80, 48, v138
	v_ashrrev_i32_e32 v81, 31, v80
	v_lshlrev_b64 v[80:81], 12, v[80:81]
	v_lshl_add_u64 v[80:81], s[26:27], 0, v[80:81]
	v_lshl_add_u64 v[88:89], v[80:81], 0, v[140:141]
	s_add_u32 s98, s26, 0x80000
	s_addc_u32 s99, s27, 0
	global_load_dwordx4 v[220:223], v189, s[98:99] offset:512
	global_load_dwordx4 v[224:227], v189, s[98:99] offset:528
	s_waitcnt vmcnt(12)
	v_pk_fma_f32 v[74:75], v[74:75], 0.5, v[234:235] op_sel_hi:[1,0,1]
	v_pk_fma_f32 v[78:79], v[78:79], 0.5, v[230:231] op_sel_hi:[1,0,1]
	v_pk_fma_f32 v[76:77], v[76:77], 0.5, v[228:229] op_sel_hi:[1,0,1]
	v_pk_fma_f32 v[72:73], v[72:73], 0.5, v[232:233] op_sel_hi:[1,0,1]
	global_store_dwordx4 v[88:89], v[76:79], off
	global_store_dwordx4 v[88:89], v[72:75], off offset:16
	s_add_u32 s98, s26, 0x90000
	s_addc_u32 s99, s27, 0
	global_load_dwordx4 v[228:231], v189, s[98:99]
	global_load_dwordx4 v[232:235], v189, s[98:99] offset:16
	s_waitcnt vmcnt(12)
	v_pk_fma_f32 v[66:67], v[66:67], 0.5, v[250:251] op_sel_hi:[1,0,1]
	v_pk_fma_f32 v[70:71], v[70:71], 0.5, v[246:247] op_sel_hi:[1,0,1]
	v_pk_fma_f32 v[68:69], v[68:69], 0.5, v[244:245] op_sel_hi:[1,0,1]
	v_add_co_u32_e32 v74, vcc, s47, v136
	v_pk_fma_f32 v[64:65], v[64:65], 0.5, v[248:249] op_sel_hi:[1,0,1]
	global_store_dwordx4 v[88:89], v[68:71], off offset:512
	global_store_dwordx4 v[88:89], v[64:67], off offset:528
	v_addc_co_u32_e32 v75, vcc, 0, v137, vcc
	v_lshl_add_u64 v[72:73], v[136:137], 0, s[14:15]
	s_add_u32 s98, s26, 0x90000
	s_addc_u32 s99, s27, 0
	global_load_dwordx4 v[244:247], v189, s[98:99] offset:512
	global_load_dwordx4 v[248:251], v189, s[98:99] offset:528
	s_waitcnt vmcnt(12)
	v_pk_fma_f32 v[62:63], v[62:63], 0.5, v[214:215] op_sel_hi:[1,0,1]
	v_pk_fma_f32 v[60:61], v[60:61], 0.5, v[212:213] op_sel_hi:[1,0,1]
	v_pk_fma_f32 v[58:59], v[58:59], 0.5, v[218:219] op_sel_hi:[1,0,1]
	v_pk_fma_f32 v[56:57], v[56:57], 0.5, v[216:217] op_sel_hi:[1,0,1]
	global_store_dwordx4 v[74:75], v[60:63], off
	global_store_dwordx4 v[72:73], v[56:59], off offset:16
	s_add_u32 s98, s26, 0xa0000
	s_addc_u32 s99, s27, 0
	global_load_dwordx4 v[212:215], v189, s[98:99]
	global_load_dwordx4 v[216:219], v189, s[98:99] offset:16
	s_waitcnt vmcnt(12)
	v_pk_fma_f32 v[50:51], v[50:51], 0.5, v[226:227] op_sel_hi:[1,0,1]
	v_pk_fma_f32 v[54:55], v[54:55], 0.5, v[222:223] op_sel_hi:[1,0,1]
	v_pk_fma_f32 v[52:53], v[52:53], 0.5, v[220:221] op_sel_hi:[1,0,1]
	v_add_co_u32_e32 v58, vcc, s48, v136
	v_pk_fma_f32 v[48:49], v[48:49], 0.5, v[224:225] op_sel_hi:[1,0,1]
	global_store_dwordx4 v[72:73], v[52:55], off offset:512
	global_store_dwordx4 v[72:73], v[48:51], off offset:528
	v_addc_co_u32_e32 v59, vcc, 0, v137, vcc
	v_lshl_add_u64 v[56:57], v[136:137], 0, s[18:19]
	s_add_u32 s98, s26, 0xa0000
	s_addc_u32 s99, s27, 0
	global_load_dwordx4 v[220:223], v189, s[98:99] offset:512
	global_load_dwordx4 v[224:227], v189, s[98:99] offset:528
	s_waitcnt vmcnt(12)
	v_pk_fma_f32 v[46:47], v[46:47], 0.5, v[230:231] op_sel_hi:[1,0,1]
	v_pk_fma_f32 v[44:45], v[44:45], 0.5, v[228:229] op_sel_hi:[1,0,1]
	v_pk_fma_f32 v[42:43], v[42:43], 0.5, v[234:235] op_sel_hi:[1,0,1]
	v_pk_fma_f32 v[40:41], v[40:41], 0.5, v[232:233] op_sel_hi:[1,0,1]
	global_store_dwordx4 v[58:59], v[44:47], off
	global_store_dwordx4 v[56:57], v[40:43], off offset:16
	s_add_u32 s98, s26, 0xb0000
	s_addc_u32 s99, s27, 0
	global_load_dwordx4 v[228:231], v189, s[98:99]
	global_load_dwordx4 v[232:235], v189, s[98:99] offset:16
	s_waitcnt vmcnt(12)
	v_pk_fma_f32 v[34:35], v[34:35], 0.5, v[250:251] op_sel_hi:[1,0,1]
	v_pk_fma_f32 v[38:39], v[38:39], 0.5, v[246:247] op_sel_hi:[1,0,1]
	v_pk_fma_f32 v[36:37], v[36:37], 0.5, v[244:245] op_sel_hi:[1,0,1]
	v_add_co_u32_e32 v42, vcc, s49, v136
	v_pk_fma_f32 v[32:33], v[32:33], 0.5, v[248:249] op_sel_hi:[1,0,1]
	global_store_dwordx4 v[56:57], v[36:39], off offset:512
	global_store_dwordx4 v[56:57], v[32:35], off offset:528
	v_addc_co_u32_e32 v43, vcc, 0, v137, vcc
	v_lshl_add_u64 v[40:41], v[136:137], 0, s[20:21]
	s_add_u32 s98, s26, 0xb0000
	s_addc_u32 s99, s27, 0
	global_load_dwordx4 v[244:247], v189, s[98:99] offset:512
	global_load_dwordx4 v[248:251], v189, s[98:99] offset:528
	s_waitcnt vmcnt(12)
	v_pk_fma_f32 v[30:31], v[30:31], 0.5, v[214:215] op_sel_hi:[1,0,1]
	v_pk_fma_f32 v[28:29], v[28:29], 0.5, v[212:213] op_sel_hi:[1,0,1]
	v_pk_fma_f32 v[26:27], v[26:27], 0.5, v[218:219] op_sel_hi:[1,0,1]
	v_pk_fma_f32 v[24:25], v[24:25], 0.5, v[216:217] op_sel_hi:[1,0,1]
	global_store_dwordx4 v[42:43], v[28:31], off
	global_store_dwordx4 v[40:41], v[24:27], off offset:16
	s_waitcnt vmcnt(10)
	v_pk_fma_f32 v[18:19], v[18:19], 0.5, v[226:227] op_sel_hi:[1,0,1]
	v_pk_fma_f32 v[22:23], v[22:23], 0.5, v[222:223] op_sel_hi:[1,0,1]
	v_pk_fma_f32 v[20:21], v[20:21], 0.5, v[220:221] op_sel_hi:[1,0,1]
	v_add_co_u32_e32 v26, vcc, s50, v136
	v_pk_fma_f32 v[16:17], v[16:17], 0.5, v[224:225] op_sel_hi:[1,0,1]
	global_store_dwordx4 v[40:41], v[20:23], off offset:512
	global_store_dwordx4 v[40:41], v[16:19], off offset:528
	v_addc_co_u32_e32 v27, vcc, 0, v137, vcc
	s_nop 0
	v_lshl_add_u64 v[16:17], v[136:137], 0, s[6:7]
	s_and_b64 vcc, exec, s[0:1]
	s_waitcnt vmcnt(8)
	v_pk_fma_f32 v[14:15], v[14:15], 0.5, v[230:231] op_sel_hi:[1,0,1]
	v_pk_fma_f32 v[12:13], v[12:13], 0.5, v[228:229] op_sel_hi:[1,0,1]
	v_pk_fma_f32 v[10:11], v[10:11], 0.5, v[234:235] op_sel_hi:[1,0,1]
	v_pk_fma_f32 v[8:9], v[8:9], 0.5, v[232:233] op_sel_hi:[1,0,1]
	global_store_dwordx4 v[26:27], v[12:15], off
	global_store_dwordx4 v[16:17], v[8:11], off offset:16
	s_waitcnt vmcnt(6)
	v_pk_fma_f32 v[2:3], v[2:3], 0.5, v[250:251] op_sel_hi:[1,0,1]
	v_pk_fma_f32 v[6:7], v[6:7], 0.5, v[246:247] op_sel_hi:[1,0,1]
	v_pk_fma_f32 v[4:5], v[4:5], 0.5, v[244:245] op_sel_hi:[1,0,1]
	v_pk_fma_f32 v[0:1], v[0:1], 0.5, v[248:249] op_sel_hi:[1,0,1]
	global_store_dwordx4 v[16:17], v[4:7], off offset:512
	global_store_dwordx4 v[16:17], v[0:3], off offset:528
	s_cbranch_vccnz .LBB0_1857
	s_andn2_b64 vcc, exec, s[8:9]
	s_cbranch_vccnz .LBB0_1856
	s_barrier
	s_branch .LBB0_1856
